# GEMM phases: no s_sleep de-phase
# baseline (speedup 1.0000x reference)
.LBB0_295:
	s_mov_b32 s0, 1
	s_cmp_ge_i32 s54, s0
	s_mov_b64 s[0:1], -1
	s_cbranch_scc1 .LBB0_294
	s_and_b64 vcc, exec, s[2:3]
	s_cbranch_vccnz .LBB0_298
	s_sleep 0

.LBB0_827:
	s_mov_b32 s6, 1
	s_cmp_ge_i32 s56, s6
	s_mov_b64 s[8:9], -1
	s_cbranch_scc1 .LBB0_826
	s_and_b64 vcc, exec, s[2:3]
	s_cbranch_vccnz .LBB0_830
	s_sleep 0

.LBB0_991:
	s_mov_b32 s6, 1
	s_cmp_lt_i32 s55, s6
	s_mov_b64 s[10:11], -1
	s_cbranch_scc0 .LBB0_990
	s_and_b64 vcc, exec, s[2:3]
	s_cbranch_vccnz .LBB0_994
	s_sleep 0

.LBB0_1060:
	s_mov_b32 s0, 1
	s_cmp_ge_i32 s59, s0
	s_mov_b64 s[8:9], -1
	s_cbranch_scc1 .LBB0_1059
	s_and_b64 vcc, exec, s[2:3]
	s_cbranch_vccnz .LBB0_1063
	s_sleep 0

.LBB0_1275:
	s_mov_b32 s0, 1
	s_cmp_ge_i32 s55, s0
	s_mov_b64 s[0:1], -1
	s_cbranch_scc1 .LBB0_1274
	s_and_b64 vcc, exec, s[2:3]
	s_cbranch_vccnz .LBB0_1278
	s_sleep 0

.LBB0_1807:
	s_mov_b32 s6, 1
	s_cmp_ge_i32 s55, s6
	s_mov_b64 s[8:9], -1
	s_cbranch_scc1 .LBB0_1806
	s_and_b64 vcc, exec, s[2:3]
	s_cbranch_vccnz .LBB0_1810
	s_sleep 0

.LBB0_2040:
	s_mov_b32 s0, 1
	s_cmp_ge_i32 s56, s0
	s_mov_b64 s[8:9], -1
	s_cbranch_scc1 .LBB0_2039
	s_and_b64 vcc, exec, s[2:3]
	s_cbranch_vccnz .LBB0_2043
	s_sleep 0
